# ssm pass 3 without the up-front touch of the unit's u rows
# baseline (speedup 1.0000x reference)
; #define PG8_STAGE(bufoff, gbase, voff) do { _Pragma("unroll") for (int _i = 0; _i < 2; ++_i) \
;         __builtin_amdgcn_global_load_lds((const unsigned*)((const char*)(gbase) + (voff)[_i]), (PG8_LAS unsigned*)(lds + (bufoff) + ldsw + _i * 8192), 16, 0, 0); } while (0)
; #define PG8_LDA(dst, b, h) do { _Pragma("unroll") for (int m = 0; m < 4; ++m) _Pragma("unroll") for (int k = 0; k < 2; ++k) dst[m][k] = *(const PG8_LAS bf16x8*)(lds + PG8_SA(b, h) + aoff + m * 2048 + k * 1024); } while (0)
; #define PG8_LDB(dst, b, h) do { _Pragma("unroll") for (int n = 0; n < 2; ++n) _Pragma("unroll") for (int k = 0; k < 2; ++k) dst[n][k] = *(const PG8_LAS bf16x8*)(lds + PG8_SB(b, h) + boff + n * 2048 + k * 1024); } while (0)
; #define PG8_WAIT_V(n) asm volatile("s_waitcnt vmcnt(" #n ")" ::: "memory")
; #define PG8_WAIT_L(n) asm volatile("s_waitcnt lgkmcnt(" #n ")" ::: "memory")
; #define PG8_BAR __builtin_amdgcn_s_barrier()
; #define PG8_SCHED __builtin_amdgcn_sched_barrier(0)
; template <class Epi, class Sched, bool ALIGN_EPI = false, bool SP2 = false>
; __device__ __forceinline__ void gemm_phase(PG8_LAS unsigned char* lds, const Gemm g, const Sched& S, const Epi& E, int wave_in) {
;     ...
;         const char* nA = has_next ? (const char*)g.A + (size_t)nxt.pm * tstepA : cA; const char* nB = has_next ? (const char*)g.Bt + (size_t)nxt.pn * tstep : cB;
;         for (int t = 0; t < nt; t += 2) {
;             const bool last = (t == nt - 2);
;             const char* a1 = cA + (size_t)(t + 1) * kstep;
;             const char* a2 = last ? nA : cA + (size_t)(t + 2) * kstep; const char* b2 = last ? nB : cB + (size_t)(t + 2) * kstep;
;             const char* a3 = a2 + kstep; const char* b3 = b2 + kstep;
;             if (last && has_next) S.a_ready(nxt);
;             if constexpr (SP2) {
;             PG8_LDB(B0, 0, 0); PG8_LDB(B1, 0, 1); PG8_SCHED; PG8_LDA(At, 0, 0); PG8_STAGE(PG8_SA(1, 1), a1 + hstepA, voffA);
;             PG8_WAIT_V(8); PG8_WAIT_L(0); PG8_BAR; PG8_MMA(0, 0, At, B0); PG8_MMA(0, 1, At, B1); PG8_BAR; PG8_SCHED;
;     ...
; #pragma unroll
;         for (int a = 0; a < 2; ++a)
; #pragma unroll
;             for (int b = 0; b < 2; ++b)
; #pragma unroll
;                 for (int m = 0; m < 4; ++m)
; #pragma unroll
;                     for (int n = 0; n < 2; ++n) acc[a][b][m][n] = (f32x4){0.f, 0.f, 0.f, 0.f};
;         cur = nxt; cA = nA; cB = nB; ++ui;
.LBB0_276:
	s_ashr_i32 s19, s18, 31
	s_lshl_b64 s[4:5], s[18:19], 20
	v_readlane_b32 s20, v253, 60
	v_readlane_b32 s21, v253, 61
	s_add_u32 s20, s20, s4
	s_load_dwordx2 s[22:23], s[82:83], 0xf8
	s_addc_u32 s21, s21, s5
	s_and_b64 s[4:5], s[6:7], exec
	s_cselect_b32 s19, s21, s1
	s_cselect_b32 s36, s20, s0
	s_ashr_i32 s17, s16, 31
	s_lshl_b64 s[4:5], s[16:17], 20
	s_waitcnt lgkmcnt(0)
	s_add_u32 s22, s22, s4
	s_addc_u32 s23, s23, s5
	s_and_b64 s[4:5], s[6:7], exec
	s_cselect_b32 s17, s23, s3
	s_cselect_b32 s37, s22, s2
	s_add_u32 s0, s0, 0x80080
	s_addc_u32 s1, s1, 0
	s_add_u32 s38, s2, 0x100
	v_mov_b32_e32 v2, 0
	s_addc_u32 s39, s3, 0
	s_mov_b32 s40, -2
	v_mov_b32_e32 v3, v2
	v_mov_b32_e32 v4, v2
	v_mov_b32_e32 v5, v2
	v_mov_b32_e32 v6, v2
	v_mov_b32_e32 v7, v2
	v_mov_b32_e32 v8, v2
	v_mov_b32_e32 v9, v2
	v_mov_b32_e32 v18, v2
	v_mov_b32_e32 v19, v2
	s_waitcnt vmcnt(0)
	v_mov_b32_e32 v20, v2
	v_mov_b32_e32 v21, v2
	v_mov_b32_e32 v22, v2
	v_mov_b32_e32 v23, v2
	v_mov_b32_e32 v24, v2
	v_mov_b32_e32 v25, v2
	v_mov_b32_e32 v50, v2
	v_mov_b32_e32 v51, v2
	v_mov_b32_e32 v52, v2
	v_mov_b32_e32 v53, v2
	v_mov_b32_e32 v54, v2
	v_mov_b32_e32 v55, v2
	v_mov_b32_e32 v56, v2
	v_mov_b32_e32 v57, v2
	v_mov_b32_e32 v66, v2
	v_mov_b32_e32 v67, v2
	v_mov_b32_e32 v68, v2
	v_mov_b32_e32 v69, v2
	v_mov_b32_e32 v70, v2
	v_mov_b32_e32 v71, v2
	v_mov_b32_e32 v72, v2
	v_mov_b32_e32 v73, v2
	v_mov_b32_e32 v10, v2
	v_mov_b32_e32 v11, v2
	v_mov_b32_e32 v12, v2
	v_mov_b32_e32 v13, v2
	v_mov_b32_e32 v14, v2
	v_mov_b32_e32 v15, v2
	v_mov_b32_e32 v16, v2
	v_mov_b32_e32 v17, v2
	v_mov_b32_e32 v34, v2
	v_mov_b32_e32 v35, v2
	v_mov_b32_e32 v36, v2
	v_mov_b32_e32 v37, v2
	v_mov_b32_e32 v38, v2
	v_mov_b32_e32 v39, v2
	v_mov_b32_e32 v40, v2
	v_mov_b32_e32 v41, v2
	v_mov_b32_e32 v58, v2
	v_mov_b32_e32 v59, v2
	v_mov_b32_e32 v60, v2
	v_mov_b32_e32 v61, v2
	v_mov_b32_e32 v62, v2
	v_mov_b32_e32 v63, v2
	v_mov_b32_e32 v64, v2
	v_mov_b32_e32 v65, v2
	v_mov_b32_e32 v74, v2
	v_mov_b32_e32 v75, v2
	v_mov_b32_e32 v76, v2
	v_mov_b32_e32 v77, v2
	v_mov_b32_e32 v78, v2
	v_mov_b32_e32 v79, v2
	v_mov_b32_e32 v80, v2
	v_mov_b32_e32 v81, v2
	v_mov_b32_e32 v82, v2
	v_mov_b32_e32 v83, v2
	v_mov_b32_e32 v84, v2
	v_mov_b32_e32 v85, v2
	v_mov_b32_e32 v86, v2
	v_mov_b32_e32 v87, v2
	v_mov_b32_e32 v88, v2
	v_mov_b32_e32 v89, v2
	v_mov_b32_e32 v98, v2
	v_mov_b32_e32 v99, v2
	v_mov_b32_e32 v100, v2
	v_mov_b32_e32 v101, v2
	v_mov_b32_e32 v102, v2
	v_mov_b32_e32 v103, v2
	v_mov_b32_e32 v104, v2
	v_mov_b32_e32 v105, v2
	v_mov_b32_e32 v114, v2
	v_mov_b32_e32 v115, v2
	v_mov_b32_e32 v116, v2
	v_mov_b32_e32 v117, v2
	v_mov_b32_e32 v118, v2
	v_mov_b32_e32 v119, v2
	v_mov_b32_e32 v120, v2
	v_mov_b32_e32 v121, v2
	v_mov_b32_e32 v130, v2
	v_mov_b32_e32 v131, v2
	v_mov_b32_e32 v132, v2
	v_mov_b32_e32 v133, v2
	v_mov_b32_e32 v134, v2
	v_mov_b32_e32 v135, v2
	v_mov_b32_e32 v136, v2
	v_mov_b32_e32 v137, v2
	v_mov_b32_e32 v90, v2
	v_mov_b32_e32 v91, v2
	v_mov_b32_e32 v92, v2
	v_mov_b32_e32 v93, v2
	v_mov_b32_e32 v94, v2
	v_mov_b32_e32 v95, v2
	v_mov_b32_e32 v96, v2
	v_mov_b32_e32 v97, v2
	v_mov_b32_e32 v106, v2
	v_mov_b32_e32 v107, v2
	v_mov_b32_e32 v108, v2
	v_mov_b32_e32 v109, v2
	v_mov_b32_e32 v110, v2
	v_mov_b32_e32 v111, v2
	v_mov_b32_e32 v112, v2
	v_mov_b32_e32 v113, v2
	v_mov_b32_e32 v122, v2
	v_mov_b32_e32 v123, v2
	v_mov_b32_e32 v124, v2
	v_mov_b32_e32 v125, v2
	v_mov_b32_e32 v126, v2
	v_mov_b32_e32 v127, v2
	v_mov_b32_e32 v128, v2
	v_mov_b32_e32 v129, v2
	v_mov_b32_e32 v138, v2
	v_mov_b32_e32 v139, v2
	v_mov_b32_e32 v140, v2
	v_mov_b32_e32 v141, v2
	v_mov_b32_e32 v142, v2
	v_mov_b32_e32 v143, v2
	v_mov_b32_e32 v144, v2
	v_mov_b32_e32 v145, v2
	s_nop 0
	s_nop 0
	s_nop 0
	s_nop 0
	s_nop 0
	s_nop 0
.LBB0_277:
	s_add_u32 s2, s0, 0xfff80080
	s_addc_u32 s3, s1, -1
	s_add_i32 s41, 0, 0x10000
	s_cmp_eq_u32 s40, 28
	s_cselect_b32 s5, s19, s3
	s_cselect_b32 s4, s36, s2
	s_cselect_b32 s3, s17, s39
	s_cselect_b32 s2, s37, s38
	s_add_i32 s44, 0, 0x14000
	v_add_u32_e32 v46, s41, v181
	v_add_u32_e32 v156, s44, v181
	ds_read_b128 v[26:29], v46
	ds_read_b128 v[30:33], v46 offset:1024
	ds_read_b128 v[42:45], v46 offset:2048
	ds_read_b128 v[46:49], v46 offset:3072
	ds_read_b128 v[168:171], v156
	ds_read_b128 v[172:175], v156 offset:1024
	ds_read_b128 v[176:179], v156 offset:2048
	ds_read_b128 v[184:187], v156 offset:3072
	s_add_i32 m0, s25, 0xc000
	ds_read_b128 v[188:191], v183
	ds_read_b128 v[212:215], v183 offset:1024
	ds_read_b128 v[216:219], v183 offset:2048
	ds_read_b128 v[220:223], v183 offset:3072
	ds_read_b128 v[224:227], v183 offset:4096
	ds_read_b128 v[228:231], v183 offset:5120
	ds_read_b128 v[232:235], v183 offset:6144
	ds_read_b128 v[236:239], v183 offset:7168
	global_load_lds_dwordx4 v152, s[0:1]
	s_add_i32 m0, s25, 0xe000
	s_nop 0
	global_load_lds_dwordx4 v154, s[0:1]
	s_waitcnt vmcnt(8)
	s_waitcnt lgkmcnt(0)
	s_barrier
; #define PG8_STAGE(bufoff, gbase, voff) do { _Pragma("unroll") for (int _i = 0; _i < 2; ++_i) \
;         __builtin_amdgcn_global_load_lds((const unsigned*)((const char*)(gbase) + (voff)[_i]), (PG8_LAS unsigned*)(lds + (bufoff) + ldsw + _i * 8192), 16, 0, 0); } while (0)
; #define PG8_LDA(dst, b, h) do { _Pragma("unroll") for (int m = 0; m < 4; ++m) _Pragma("unroll") for (int k = 0; k < 2; ++k) dst[m][k] = *(const PG8_LAS bf16x8*)(lds + PG8_SA(b, h) + aoff + m * 2048 + k * 1024); } while (0)
; #define PG8_MMA(ai, bj, At, Bt) do { __builtin_amdgcn_s_setprio(1); _Pragma("unroll") for (int m = 0; m < 4; ++m) _Pragma("unroll") for (int n = 0; n < 2; ++n) _Pragma("unroll") for (int k = 0; k < 2; ++k) \
;         acc[ai][bj][m][n] = __builtin_amdgcn_mfma_f32_16x16x32_bf16(Bt[n][k], At[m][k], acc[ai][bj][m][n], 0, 0, 0); __builtin_amdgcn_s_setprio(0); } while (0)
; #define PG8_WAIT_V(n) asm volatile("s_waitcnt vmcnt(" #n ")" ::: "memory")
; #define PG8_WAIT_L(n) asm volatile("s_waitcnt lgkmcnt(" #n ")" ::: "memory")
; #define PG8_BAR __builtin_amdgcn_s_barrier()
; #define PG8_SCHED __builtin_amdgcn_sched_barrier(0)
; template <class Epi, class Sched, bool ALIGN_EPI = false, bool SP2 = false>
; __device__ __forceinline__ void gemm_phase(PG8_LAS unsigned char* lds, const Gemm g, const Sched& S, const Epi& E, int wave_in) {
;     ...
;             PG8_WAIT_V(8); PG8_WAIT_L(0); PG8_BAR; PG8_MMA(0, 0, At, B0); PG8_MMA(0, 1, At, B1); PG8_BAR; PG8_SCHED;
;             PG8_LDA(At, 0, 1); PG8_STAGE(PG8_SB(0, 0), b2, voffB); PG8_STAGE(PG8_SB(0, 1), b2 + hstep, voffB); PG8_STAGE(PG8_SA(0, 0), a2, voffA);
;             PG8_WAIT_V(8); PG8_WAIT_L(0); PG8_BAR; PG8_MMA(1, 0, At, B0); PG8_MMA(1, 1, At, B1); PG8_BAR; PG8_SCHED;
	s_waitcnt lgkmcnt(0)
	v_mfma_f32_16x16x32_bf16 v[142:145], v[26:29], v[188:191], v[142:145]
	v_mfma_f32_16x16x32_bf16 v[138:141], v[42:45], v[188:191], v[138:141]
	v_mfma_f32_16x16x32_bf16 v[126:129], v[26:29], v[216:219], v[126:129]
	v_mfma_f32_16x16x32_bf16 v[122:125], v[42:45], v[216:219], v[122:125]
	v_mfma_f32_16x16x32_bf16 v[110:113], v[26:29], v[224:227], v[110:113]
	v_mfma_f32_16x16x32_bf16 v[106:109], v[42:45], v[224:227], v[106:109]
	v_mfma_f32_16x16x32_bf16 v[94:97], v[26:29], v[232:235], v[94:97]
	v_mfma_f32_16x16x32_bf16 v[90:93], v[42:45], v[232:235], v[90:93]
	v_mfma_f32_16x16x32_bf16 v[142:145], v[30:33], v[212:215], v[142:145]
	v_mfma_f32_16x16x32_bf16 v[138:141], v[46:49], v[212:215], v[138:141]
	v_mfma_f32_16x16x32_bf16 v[126:129], v[30:33], v[220:223], v[126:129]
	v_mfma_f32_16x16x32_bf16 v[122:125], v[46:49], v[220:223], v[122:125]
	v_mfma_f32_16x16x32_bf16 v[110:113], v[30:33], v[228:231], v[110:113]
	v_mfma_f32_16x16x32_bf16 v[106:109], v[46:49], v[228:231], v[106:109]
	v_mfma_f32_16x16x32_bf16 v[94:97], v[30:33], v[236:239], v[94:97]
	v_mfma_f32_16x16x32_bf16 v[90:93], v[46:49], v[236:239], v[90:93]
	v_mfma_f32_16x16x32_bf16 v[134:137], v[168:171], v[188:191], v[134:137]
	v_mfma_f32_16x16x32_bf16 v[130:133], v[176:179], v[188:191], v[130:133]
	v_mfma_f32_16x16x32_bf16 v[118:121], v[168:171], v[216:219], v[118:121]
	v_mfma_f32_16x16x32_bf16 v[114:117], v[176:179], v[216:219], v[114:117]
	v_mfma_f32_16x16x32_bf16 v[102:105], v[168:171], v[224:227], v[102:105]
	v_mfma_f32_16x16x32_bf16 v[98:101], v[176:179], v[224:227], v[98:101]
	v_mfma_f32_16x16x32_bf16 v[86:89], v[168:171], v[232:235], v[86:89]
	v_mfma_f32_16x16x32_bf16 v[82:85], v[176:179], v[232:235], v[82:85]
	v_mfma_f32_16x16x32_bf16 v[134:137], v[172:175], v[212:215], v[134:137]
	v_mfma_f32_16x16x32_bf16 v[130:133], v[184:187], v[212:215], v[130:133]
	v_mfma_f32_16x16x32_bf16 v[118:121], v[172:175], v[220:223], v[118:121]
	v_mfma_f32_16x16x32_bf16 v[114:117], v[184:187], v[220:223], v[114:117]
	v_mfma_f32_16x16x32_bf16 v[102:105], v[172:175], v[228:231], v[102:105]
	v_mfma_f32_16x16x32_bf16 v[98:101], v[184:187], v[228:231], v[98:101]
	v_mfma_f32_16x16x32_bf16 v[86:89], v[172:175], v[236:239], v[86:89]
	v_mfma_f32_16x16x32_bf16 v[82:85], v[184:187], v[236:239], v[82:85]
	s_barrier
	s_add_i32 s41, s41, s24
	s_add_u32 vcc_lo, s2, s84
	s_addc_u32 vcc_hi, s3, s85
	s_mov_b32 m0, s41
	ds_read_b128 v[188:191], v183 offset:16384
	ds_read_b128 v[212:215], v183 offset:17408
	ds_read_b128 v[216:219], v183 offset:18432
	ds_read_b128 v[220:223], v183 offset:19456
	ds_read_b128 v[224:227], v183 offset:20480
	ds_read_b128 v[228:231], v183 offset:21504
	ds_read_b128 v[232:235], v183 offset:22528
	ds_read_b128 v[236:239], v183 offset:23552
	global_load_lds_dwordx4 v0, s[2:3]
	s_add_i32 m0, s41, 0x2000
	s_add_u32 s42, s2, 0x80000
	s_addc_u32 s43, s3, 0
	s_add_i32 s41, s44, s24
	global_load_lds_dwordx4 v146, s[2:3]
	s_mov_b32 m0, s41
	s_add_u32 s98, s4, s84
	s_addc_u32 s99, s5, s85
	global_load_lds_dwordx4 v0, s[42:43]
	s_add_i32 m0, s41, 0x2000
	s_nop 0
	global_load_lds_dwordx4 v146, s[42:43]
	s_mov_b32 m0, s25
	s_nop 0
	global_load_lds_dwordx4 v150, s[4:5]
	s_mov_b32 m0, s26
	s_nop 0
	global_load_lds_dwordx4 v148, s[4:5]
	s_waitcnt vmcnt(8)
	s_waitcnt lgkmcnt(0)
	s_barrier
	s_waitcnt lgkmcnt(0)
	v_mfma_f32_16x16x32_bf16 v[78:81], v[26:29], v[188:191], v[78:81]
	v_mfma_f32_16x16x32_bf16 v[74:77], v[42:45], v[188:191], v[74:77]
	v_mfma_f32_16x16x32_bf16 v[62:65], v[26:29], v[216:219], v[62:65]
	v_mfma_f32_16x16x32_bf16 v[58:61], v[42:45], v[216:219], v[58:61]
	v_mfma_f32_16x16x32_bf16 v[38:41], v[26:29], v[224:227], v[38:41]
	v_mfma_f32_16x16x32_bf16 v[34:37], v[42:45], v[224:227], v[34:37]
	v_mfma_f32_16x16x32_bf16 v[14:17], v[26:29], v[232:235], v[14:17]
	v_mfma_f32_16x16x32_bf16 v[10:13], v[42:45], v[232:235], v[10:13]
	v_mfma_f32_16x16x32_bf16 v[78:81], v[30:33], v[212:215], v[78:81]
	v_mfma_f32_16x16x32_bf16 v[74:77], v[46:49], v[212:215], v[74:77]
	v_mfma_f32_16x16x32_bf16 v[62:65], v[30:33], v[220:223], v[62:65]
	v_mfma_f32_16x16x32_bf16 v[58:61], v[46:49], v[220:223], v[58:61]
	v_mfma_f32_16x16x32_bf16 v[38:41], v[30:33], v[228:231], v[38:41]
	v_mfma_f32_16x16x32_bf16 v[34:37], v[46:49], v[228:231], v[34:37]
	v_mfma_f32_16x16x32_bf16 v[14:17], v[30:33], v[236:239], v[14:17]
	v_mfma_f32_16x16x32_bf16 v[10:13], v[46:49], v[236:239], v[10:13]
	v_mfma_f32_16x16x32_bf16 v[22:25], v[168:171], v[224:227], v[22:25]
	v_mfma_f32_16x16x32_bf16 v[18:21], v[176:179], v[224:227], v[18:21]
	v_mfma_f32_16x16x32_bf16 v[6:9], v[168:171], v[232:235], v[6:9]
	v_mfma_f32_16x16x32_bf16 v[2:5], v[176:179], v[232:235], v[2:5]
	v_mfma_f32_16x16x32_bf16 v[26:29], v[168:171], v[188:191], v[70:73]
	v_mfma_f32_16x16x32_bf16 v[30:33], v[176:179], v[188:191], v[66:69]
	v_mfma_f32_16x16x32_bf16 v[42:45], v[168:171], v[216:219], v[54:57]
	v_mfma_f32_16x16x32_bf16 v[46:49], v[176:179], v[216:219], v[50:53]
	v_mfma_f32_16x16x32_bf16 v[22:25], v[172:175], v[228:231], v[22:25]
	v_mfma_f32_16x16x32_bf16 v[18:21], v[184:187], v[228:231], v[18:21]
	v_mfma_f32_16x16x32_bf16 v[6:9], v[172:175], v[236:239], v[6:9]
	v_mfma_f32_16x16x32_bf16 v[2:5], v[184:187], v[236:239], v[2:5]
	v_mfma_f32_16x16x32_bf16 v[26:29], v[172:175], v[212:215], v[26:29]
	v_mfma_f32_16x16x32_bf16 v[30:33], v[184:187], v[212:215], v[30:33]
	v_mfma_f32_16x16x32_bf16 v[42:45], v[172:175], v[220:223], v[42:45]
	v_mfma_f32_16x16x32_bf16 v[46:49], v[184:187], v[220:223], v[46:49]
	s_barrier
; #define PG8_STAGE(bufoff, gbase, voff) do { _Pragma("unroll") for (int _i = 0; _i < 2; ++_i) \
;         __builtin_amdgcn_global_load_lds((const unsigned*)((const char*)(gbase) + (voff)[_i]), (PG8_LAS unsigned*)(lds + (bufoff) + ldsw + _i * 8192), 16, 0, 0); } while (0)
; #define PG8_LDA(dst, b, h) do { _Pragma("unroll") for (int m = 0; m < 4; ++m) _Pragma("unroll") for (int k = 0; k < 2; ++k) dst[m][k] = *(const PG8_LAS bf16x8*)(lds + PG8_SA(b, h) + aoff + m * 2048 + k * 1024); } while (0)
; #define PG8_LDB(dst, b, h) do { _Pragma("unroll") for (int n = 0; n < 2; ++n) _Pragma("unroll") for (int k = 0; k < 2; ++k) dst[n][k] = *(const PG8_LAS bf16x8*)(lds + PG8_SB(b, h) + boff + n * 2048 + k * 1024); } while (0)
; #define PG8_MMA(ai, bj, At, Bt) do { __builtin_amdgcn_s_setprio(1); _Pragma("unroll") for (int m = 0; m < 4; ++m) _Pragma("unroll") for (int n = 0; n < 2; ++n) _Pragma("unroll") for (int k = 0; k < 2; ++k) \
;         acc[ai][bj][m][n] = __builtin_amdgcn_mfma_f32_16x16x32_bf16(Bt[n][k], At[m][k], acc[ai][bj][m][n], 0, 0, 0); __builtin_amdgcn_s_setprio(0); } while (0)
; #define PG8_WAIT_V(n) asm volatile("s_waitcnt vmcnt(" #n ")" ::: "memory")
; #define PG8_WAIT_L(n) asm volatile("s_waitcnt lgkmcnt(" #n ")" ::: "memory")
; #define PG8_BAR __builtin_amdgcn_s_barrier()
; template <class Epi, class Sched, bool ALIGN_EPI = false, bool SP2 = false>
; __device__ __forceinline__ void gemm_phase(PG8_LAS unsigned char* lds, const Gemm g, const Sched& S, const Epi& E, int wave_in) {
;     ...
;         for (int t = 0; t < nt; t += 2) {
;             const bool last = (t == nt - 2);
;             const char* a1 = cA + (size_t)(t + 1) * kstep;
;             const char* a2 = last ? nA : cA + (size_t)(t + 2) * kstep; const char* b2 = last ? nB : cB + (size_t)(t + 2) * kstep;
;             const char* a3 = a2 + kstep; const char* b3 = b2 + kstep;
;     ...
;             PG8_LDB(B0, 1, 0); PG8_LDB(B1, 1, 1); PG8_SCHED; PG8_LDA(At, 1, 0); PG8_STAGE(PG8_SA(0, 1), a2 + hstepA, voffA);
;             PG8_WAIT_V(8); PG8_WAIT_L(0); PG8_BAR; PG8_MMA(0, 0, At, B0); PG8_MMA(0, 1, At, B1); PG8_BAR; PG8_SCHED;
;             PG8_LDA(At, 1, 1); PG8_STAGE(PG8_SB(1, 0), b3, voffB); PG8_STAGE(PG8_SB(1, 1), b3 + hstep, voffB); PG8_STAGE(PG8_SA(1, 0), a3, voffA);
;             PG8_WAIT_V(8); PG8_WAIT_L(0); PG8_BAR; PG8_MMA(1, 0, At, B0); PG8_MMA(1, 1, At, B1); PG8_BAR; PG8_SCHED;
	s_add_i32 s41, 0, 0x18000
	s_add_i32 s42, 0, 0x1c000
	v_add_u32_e32 v70, s41, v181
	v_add_u32_e32 v184, s42, v181
	ds_read_b128 v[50:53], v70
	ds_read_b128 v[54:57], v70 offset:1024
	ds_read_b128 v[66:69], v70 offset:2048
	ds_read_b128 v[70:73], v70 offset:3072
	ds_read_b128 v[168:171], v184
	ds_read_b128 v[172:175], v184 offset:1024
	ds_read_b128 v[176:179], v184 offset:2048
	ds_read_b128 v[184:187], v184 offset:3072
	s_add_u32 s4, s4, 0x80000
	s_addc_u32 s5, s5, 0
	s_mov_b32 m0, s27
	ds_read_b128 v[188:191], v183 offset:32768
	ds_read_b128 v[212:215], v183 offset:33792
	ds_read_b128 v[216:219], v183 offset:34816
	ds_read_b128 v[220:223], v183 offset:35840
	ds_read_b128 v[224:227], v183 offset:36864
	ds_read_b128 v[228:231], v183 offset:37888
	ds_read_b128 v[232:235], v183 offset:38912
	ds_read_b128 v[236:239], v183 offset:39936
	global_load_lds_dwordx4 v150, s[4:5]
	s_mov_b32 m0, s28
	s_nop 0
	global_load_lds_dwordx4 v148, s[4:5]
	s_waitcnt vmcnt(8)
	s_waitcnt lgkmcnt(0)
	s_barrier
	s_waitcnt lgkmcnt(0)
	v_mfma_f32_16x16x32_bf16 v[142:145], v[50:53], v[188:191], v[142:145]
	v_mfma_f32_16x16x32_bf16 v[138:141], v[66:69], v[188:191], v[138:141]
	v_mfma_f32_16x16x32_bf16 v[126:129], v[50:53], v[216:219], v[126:129]
	v_mfma_f32_16x16x32_bf16 v[122:125], v[66:69], v[216:219], v[122:125]
	v_mfma_f32_16x16x32_bf16 v[110:113], v[50:53], v[224:227], v[110:113]
	v_mfma_f32_16x16x32_bf16 v[106:109], v[66:69], v[224:227], v[106:109]
	v_mfma_f32_16x16x32_bf16 v[94:97], v[50:53], v[232:235], v[94:97]
	v_mfma_f32_16x16x32_bf16 v[90:93], v[66:69], v[232:235], v[90:93]
	v_mfma_f32_16x16x32_bf16 v[142:145], v[54:57], v[212:215], v[142:145]
	v_mfma_f32_16x16x32_bf16 v[138:141], v[70:73], v[212:215], v[138:141]
	v_mfma_f32_16x16x32_bf16 v[126:129], v[54:57], v[220:223], v[126:129]
	v_mfma_f32_16x16x32_bf16 v[122:125], v[70:73], v[220:223], v[122:125]
	v_mfma_f32_16x16x32_bf16 v[110:113], v[54:57], v[228:231], v[110:113]
	v_mfma_f32_16x16x32_bf16 v[106:109], v[70:73], v[228:231], v[106:109]
	v_mfma_f32_16x16x32_bf16 v[94:97], v[54:57], v[236:239], v[94:97]
	v_mfma_f32_16x16x32_bf16 v[90:93], v[70:73], v[236:239], v[90:93]
	v_mfma_f32_16x16x32_bf16 v[134:137], v[168:171], v[188:191], v[134:137]
	v_mfma_f32_16x16x32_bf16 v[130:133], v[176:179], v[188:191], v[130:133]
	v_mfma_f32_16x16x32_bf16 v[118:121], v[168:171], v[216:219], v[118:121]
	v_mfma_f32_16x16x32_bf16 v[114:117], v[176:179], v[216:219], v[114:117]
	v_mfma_f32_16x16x32_bf16 v[102:105], v[168:171], v[224:227], v[102:105]
	v_mfma_f32_16x16x32_bf16 v[98:101], v[176:179], v[224:227], v[98:101]
	v_mfma_f32_16x16x32_bf16 v[86:89], v[168:171], v[232:235], v[86:89]
	v_mfma_f32_16x16x32_bf16 v[82:85], v[176:179], v[232:235], v[82:85]
	v_mfma_f32_16x16x32_bf16 v[134:137], v[172:175], v[212:215], v[134:137]
	v_mfma_f32_16x16x32_bf16 v[130:133], v[184:187], v[212:215], v[130:133]
	v_mfma_f32_16x16x32_bf16 v[118:121], v[172:175], v[220:223], v[118:121]
	v_mfma_f32_16x16x32_bf16 v[114:117], v[184:187], v[220:223], v[114:117]
	v_mfma_f32_16x16x32_bf16 v[102:105], v[172:175], v[228:231], v[102:105]
	v_mfma_f32_16x16x32_bf16 v[98:101], v[184:187], v[228:231], v[98:101]
	v_mfma_f32_16x16x32_bf16 v[86:89], v[172:175], v[236:239], v[86:89]
	v_mfma_f32_16x16x32_bf16 v[82:85], v[184:187], v[236:239], v[82:85]
	s_barrier
	s_add_i32 s4, s41, s24
	s_mov_b32 m0, s4
	ds_read_b128 v[188:191], v183 offset:49152
	ds_read_b128 v[212:215], v183 offset:50176
	ds_read_b128 v[216:219], v183 offset:51200
	ds_read_b128 v[220:223], v183 offset:52224
	ds_read_b128 v[224:227], v183 offset:53248
	ds_read_b128 v[228:231], v183 offset:54272
	ds_read_b128 v[232:235], v183 offset:55296
	ds_read_b128 v[236:239], v183 offset:56320
	global_load_lds_dwordx4 v0, vcc
	s_add_i32 m0, s4, 0x2000
	s_add_u32 s2, s2, 0x80080
	s_addc_u32 s3, s3, 0
	s_add_i32 s4, s42, s24
	global_load_lds_dwordx4 v146, vcc
	s_mov_b32 m0, s4
	s_nop 0
	global_load_lds_dwordx4 v0, s[2:3]
	s_add_i32 m0, s4, 0x2000
	s_nop 0
	global_load_lds_dwordx4 v146, s[2:3]
	s_mov_b32 m0, s29
	s_nop 0
	global_load_lds_dwordx4 v150, s[98:99]
	s_mov_b32 m0, s30
	s_nop 0
	global_load_lds_dwordx4 v148, s[98:99]
	s_waitcnt vmcnt(8)
	s_waitcnt lgkmcnt(0)
	s_barrier
	s_waitcnt lgkmcnt(0)
	v_mfma_f32_16x16x32_bf16 v[78:81], v[50:53], v[188:191], v[78:81]
	v_mfma_f32_16x16x32_bf16 v[74:77], v[66:69], v[188:191], v[74:77]
	v_mfma_f32_16x16x32_bf16 v[62:65], v[50:53], v[216:219], v[62:65]
	v_mfma_f32_16x16x32_bf16 v[58:61], v[66:69], v[216:219], v[58:61]
	v_mfma_f32_16x16x32_bf16 v[38:41], v[50:53], v[224:227], v[38:41]
	v_mfma_f32_16x16x32_bf16 v[34:37], v[66:69], v[224:227], v[34:37]
	v_mfma_f32_16x16x32_bf16 v[14:17], v[50:53], v[232:235], v[14:17]
	v_mfma_f32_16x16x32_bf16 v[10:13], v[66:69], v[232:235], v[10:13]
	v_mfma_f32_16x16x32_bf16 v[78:81], v[54:57], v[212:215], v[78:81]
	v_mfma_f32_16x16x32_bf16 v[74:77], v[70:73], v[212:215], v[74:77]
	v_mfma_f32_16x16x32_bf16 v[62:65], v[54:57], v[220:223], v[62:65]
	v_mfma_f32_16x16x32_bf16 v[58:61], v[70:73], v[220:223], v[58:61]
	v_mfma_f32_16x16x32_bf16 v[38:41], v[54:57], v[228:231], v[38:41]
	v_mfma_f32_16x16x32_bf16 v[34:37], v[70:73], v[228:231], v[34:37]
	v_mfma_f32_16x16x32_bf16 v[14:17], v[54:57], v[236:239], v[14:17]
	v_mfma_f32_16x16x32_bf16 v[10:13], v[70:73], v[236:239], v[10:13]
	v_mfma_f32_16x16x32_bf16 v[26:29], v[168:171], v[188:191], v[26:29]
	v_mfma_f32_16x16x32_bf16 v[70:73], v[172:175], v[212:215], v[26:29]
	v_mfma_f32_16x16x32_bf16 v[26:29], v[176:179], v[188:191], v[30:33]
	v_mfma_f32_16x16x32_bf16 v[66:69], v[184:187], v[212:215], v[26:29]
	v_mfma_f32_16x16x32_bf16 v[26:29], v[168:171], v[216:219], v[42:45]
	v_mfma_f32_16x16x32_bf16 v[54:57], v[172:175], v[220:223], v[26:29]
	v_mfma_f32_16x16x32_bf16 v[26:29], v[176:179], v[216:219], v[46:49]
	v_mfma_f32_16x16x32_bf16 v[22:25], v[168:171], v[224:227], v[22:25]
	v_mfma_f32_16x16x32_bf16 v[18:21], v[176:179], v[224:227], v[18:21]
	v_mfma_f32_16x16x32_bf16 v[6:9], v[168:171], v[232:235], v[6:9]
	v_mfma_f32_16x16x32_bf16 v[2:5], v[176:179], v[232:235], v[2:5]
	v_mfma_f32_16x16x32_bf16 v[50:53], v[184:187], v[220:223], v[26:29]
	v_mfma_f32_16x16x32_bf16 v[22:25], v[172:175], v[228:231], v[22:25]
	v_mfma_f32_16x16x32_bf16 v[18:21], v[184:187], v[228:231], v[18:21]
	v_mfma_f32_16x16x32_bf16 v[6:9], v[172:175], v[236:239], v[6:9]
	v_mfma_f32_16x16x32_bf16 v[2:5], v[184:187], v[236:239], v[2:5]
	s_barrier
	s_add_i32 s40, s40, 2
	s_add_u32 s0, s0, 0x100
	s_addc_u32 s1, s1, 0
	s_add_u32 s38, s38, 0x100
	s_addc_u32 s39, s39, 0
	s_cmp_gt_u32 s40, 29
	s_cbranch_scc0 .LBB0_277
	s_and_b64 vcc, exec, s[14:15]
	s_cbranch_vccz .LBB0_280
	s_barrier
